# DMA K-loops + attention fold: the four attn_out read-modify-write loads of a head issued together (counted waits) instead of serialized round trips
# speedup vs baseline: 1.0277x; 1.0062x over previous
.LBB0_328:
	s_waitcnt vmcnt(3)
	v_lshl_add_u64 v[2:3], s[36:37], 2, v[130:131]
	global_load_dword v0, v[2:3], off offset:8
	v_cmp_lt_i32_e32 vcc, v185, v183
	s_xor_b64 s[28:29], s[92:93], -1
	s_mov_b64 s[92:93], 0
	v_cndmask_b32_e32 v2, v182, v185, vcc
	v_lshlrev_b32_e32 v106, 2, v2
	ds_bpermute_b32 v2, v106, v165
	v_cmp_lt_i32_e32 vcc, v184, v183
	s_waitcnt lgkmcnt(0)
	v_add_f32_e32 v2, v165, v2
	v_cndmask_b32_e32 v3, v182, v184, vcc
	v_lshlrev_b32_e32 v107, 2, v3
	ds_bpermute_b32 v3, v107, v2
	s_waitcnt lgkmcnt(0)
	v_add_f32_e32 v2, v2, v3
	v_div_scale_f32 v3, s[40:41], v2, v2, 1.0
	v_rcp_f32_e32 v4, v3
	v_cmp_lt_f32_e64 s[0:1], 0, v2
	s_mov_b32 s40, 1
	v_fma_f32 v5, -v3, v4, 1.0
	v_fmac_f32_e32 v4, v5, v4
	v_div_scale_f32 v5, vcc, 1.0, v2, 1.0
	s_waitcnt vmcnt(3)
	v_mul_f32_e32 v6, v5, v4
	v_fma_f32 v7, -v3, v6, v5
	v_fmac_f32_e32 v6, v7, v4
	v_fma_f32 v3, -v3, v6, v5
	v_div_fmas_f32 v3, v3, v4, v6
	v_div_fixup_f32 v2, v3, v2, 1.0
	v_cndmask_b32_e64 v2, 0, v2, s[0:1]
	s_waitcnt vmcnt(0)
	v_mul_f32_e32 v0, v0, v2
	v_lshl_add_u64 v[2:3], s[94:95], 1, v[136:137]
	global_load_dwordx2 v[4:5], v[2:3], off
	global_load_dwordx2 v[8:9], v[2:3], off offset:32
	global_load_dwordx2 v[10:11], v[2:3], off offset:64
	global_load_dwordx2 v[12:13], v[2:3], off offset:96
	s_waitcnt vmcnt(3)
	v_lshlrev_b32_e32 v6, 16, v4
	v_and_b32_e32 v7, 0xffff0000, v4
	v_lshlrev_b32_e32 v4, 16, v5
	v_and_b32_e32 v5, 0xffff0000, v5
	v_pk_fma_f32 v[6:7], v[94:95], v[0:1], v[6:7] op_sel_hi:[1,0,1]
	v_pk_fma_f32 v[4:5], v[96:97], v[0:1], v[4:5] op_sel_hi:[1,0,1]
	v_cvt_pk_bf16_f32 v6, v6, v7
	v_cvt_pk_bf16_f32 v7, v4, v5
	global_store_dwordx2 v[2:3], v[6:7], off
	s_waitcnt vmcnt(3)
	v_lshlrev_b32_e32 v6, 16, v8
	v_and_b32_e32 v7, 0xffff0000, v8
	v_lshlrev_b32_e32 v8, 16, v9
	v_and_b32_e32 v9, 0xffff0000, v9
	v_pk_fma_f32 v[6:7], v[90:91], v[0:1], v[6:7] op_sel_hi:[1,0,1]
	v_pk_fma_f32 v[8:9], v[92:93], v[0:1], v[8:9] op_sel_hi:[1,0,1]
	v_cvt_pk_bf16_f32 v6, v6, v7
	v_cvt_pk_bf16_f32 v7, v8, v9
	global_store_dwordx2 v[2:3], v[6:7], off offset:32
	s_waitcnt vmcnt(3)
	v_lshlrev_b32_e32 v6, 16, v10
	v_and_b32_e32 v7, 0xffff0000, v10
	v_lshlrev_b32_e32 v10, 16, v11
	v_and_b32_e32 v11, 0xffff0000, v11
	v_pk_fma_f32 v[6:7], v[86:87], v[0:1], v[6:7] op_sel_hi:[1,0,1]
	v_pk_fma_f32 v[10:11], v[88:89], v[0:1], v[10:11] op_sel_hi:[1,0,1]
	v_cvt_pk_bf16_f32 v6, v6, v7
	v_cvt_pk_bf16_f32 v7, v10, v11
	global_store_dwordx2 v[2:3], v[6:7], off offset:64
	s_waitcnt vmcnt(3)
	v_lshlrev_b32_e32 v6, 16, v12
	v_and_b32_e32 v7, 0xffff0000, v12
	v_lshlrev_b32_e32 v12, 16, v13
	v_and_b32_e32 v13, 0xffff0000, v13
	v_pk_fma_f32 v[6:7], v[82:83], v[0:1], v[6:7] op_sel_hi:[1,0,1]
	v_pk_fma_f32 v[12:13], v[84:85], v[0:1], v[12:13] op_sel_hi:[1,0,1]
	v_cvt_pk_bf16_f32 v6, v6, v7
	v_cvt_pk_bf16_f32 v7, v12, v13
	global_store_dwordx2 v[2:3], v[6:7], off offset:96
	v_lshl_add_u64 v[2:3], s[74:75], 2, v[130:131]
	global_load_dword v0, v[2:3], off offset:8
	ds_bpermute_b32 v2, v106, v164
	s_waitcnt lgkmcnt(0)
	v_add_f32_e32 v2, v164, v2
	ds_bpermute_b32 v3, v107, v2
	s_waitcnt lgkmcnt(0)
	v_add_f32_e32 v2, v2, v3
	v_div_scale_f32 v3, s[42:43], v2, v2, 1.0
	v_rcp_f32_e32 v4, v3
	v_cmp_lt_f32_e64 s[0:1], 0, v2
	v_fma_f32 v5, -v3, v4, 1.0
	v_fmac_f32_e32 v4, v5, v4
	v_div_scale_f32 v5, vcc, 1.0, v2, 1.0
	v_mul_f32_e32 v6, v5, v4
	v_fma_f32 v7, -v3, v6, v5
	v_fmac_f32_e32 v6, v7, v4
	v_fma_f32 v3, -v3, v6, v5
	v_div_fmas_f32 v3, v3, v4, v6
	v_div_fixup_f32 v2, v3, v2, 1.0
	v_cndmask_b32_e64 v2, 0, v2, s[0:1]
	s_and_b64 vcc, exec, s[28:29]
	s_waitcnt vmcnt(0)
	v_mul_f32_e32 v0, v0, v2
	v_lshl_add_u64 v[2:3], s[96:97], 1, v[136:137]
	global_load_dwordx2 v[4:5], v[2:3], off
	global_load_dwordx2 v[8:9], v[2:3], off offset:32
	global_load_dwordx2 v[10:11], v[2:3], off offset:64
	global_load_dwordx2 v[12:13], v[2:3], off offset:96
	s_waitcnt vmcnt(3)
	v_lshlrev_b32_e32 v6, 16, v4
	v_and_b32_e32 v7, 0xffff0000, v4
	v_lshlrev_b32_e32 v4, 16, v5
	v_and_b32_e32 v5, 0xffff0000, v5
	v_pk_fma_f32 v[6:7], v[78:79], v[0:1], v[6:7] op_sel_hi:[1,0,1]
	v_pk_fma_f32 v[4:5], v[80:81], v[0:1], v[4:5] op_sel_hi:[1,0,1]
	v_cvt_pk_bf16_f32 v6, v6, v7
	v_cvt_pk_bf16_f32 v7, v4, v5
	global_store_dwordx2 v[2:3], v[6:7], off
	s_waitcnt vmcnt(3)
	v_lshlrev_b32_e32 v6, 16, v8
	v_and_b32_e32 v7, 0xffff0000, v8
	v_lshlrev_b32_e32 v8, 16, v9
	v_and_b32_e32 v9, 0xffff0000, v9
	v_pk_fma_f32 v[6:7], v[74:75], v[0:1], v[6:7] op_sel_hi:[1,0,1]
	v_pk_fma_f32 v[8:9], v[76:77], v[0:1], v[8:9] op_sel_hi:[1,0,1]
	v_cvt_pk_bf16_f32 v6, v6, v7
	v_cvt_pk_bf16_f32 v7, v8, v9
	global_store_dwordx2 v[2:3], v[6:7], off offset:32
	s_waitcnt vmcnt(3)
	v_lshlrev_b32_e32 v6, 16, v10
	v_and_b32_e32 v7, 0xffff0000, v10
	v_lshlrev_b32_e32 v10, 16, v11
	v_and_b32_e32 v11, 0xffff0000, v11
	v_pk_fma_f32 v[6:7], v[70:71], v[0:1], v[6:7] op_sel_hi:[1,0,1]
	v_pk_fma_f32 v[10:11], v[72:73], v[0:1], v[10:11] op_sel_hi:[1,0,1]
	v_cvt_pk_bf16_f32 v6, v6, v7
	v_cvt_pk_bf16_f32 v7, v10, v11
	global_store_dwordx2 v[2:3], v[6:7], off offset:64
	s_waitcnt vmcnt(3)
	v_lshlrev_b32_e32 v6, 16, v12
	v_and_b32_e32 v7, 0xffff0000, v12
	v_lshlrev_b32_e32 v12, 16, v13
	v_and_b32_e32 v13, 0xffff0000, v13
	v_pk_fma_f32 v[6:7], v[66:67], v[0:1], v[6:7] op_sel_hi:[1,0,1]
	v_pk_fma_f32 v[12:13], v[68:69], v[0:1], v[12:13] op_sel_hi:[1,0,1]
	v_cvt_pk_bf16_f32 v6, v6, v7
	v_cvt_pk_bf16_f32 v7, v12, v13
	global_store_dwordx2 v[2:3], v[6:7], off offset:96
	s_barrier
	s_cbranch_vccnz .LBB0_358

.LBB0_389:
	s_mul_i32 s36, s17, 6
	s_waitcnt vmcnt(3)
	v_lshl_add_u64 v[2:3], s[36:37], 2, v[130:131]
	global_load_dword v0, v[2:3], off offset:4
	ds_bpermute_b32 v2, v106, v118
	s_lshl_b32 s36, s27, 1
	s_mov_b32 s17, 1
	s_waitcnt lgkmcnt(0)
	v_add_f32_e32 v2, v118, v2
	ds_bpermute_b32 v3, v107, v2
	s_waitcnt lgkmcnt(0)
	v_add_f32_e32 v2, v2, v3
	v_div_scale_f32 v3, s[30:31], v2, v2, 1.0
	v_rcp_f32_e32 v4, v3
	v_cmp_lt_f32_e64 s[0:1], 0, v2
	v_fma_f32 v5, -v3, v4, 1.0
	v_fmac_f32_e32 v4, v5, v4
	v_div_scale_f32 v5, vcc, 1.0, v2, 1.0
	s_waitcnt vmcnt(3)
	v_mul_f32_e32 v6, v5, v4
	v_fma_f32 v7, -v3, v6, v5
	v_fmac_f32_e32 v6, v7, v4
	v_fma_f32 v3, -v3, v6, v5
	v_div_fmas_f32 v3, v3, v4, v6
	v_div_fixup_f32 v2, v3, v2, 1.0
	v_cndmask_b32_e64 v2, 0, v2, s[0:1]
	s_waitcnt vmcnt(0)
	v_mul_f32_e32 v0, v0, v2
	v_lshl_add_u64 v[2:3], v[136:137], 0, s[36:37]
	global_load_dwordx2 v[4:5], v[2:3], off
	global_load_dwordx2 v[8:9], v[2:3], off offset:32
	global_load_dwordx2 v[10:11], v[2:3], off offset:64
	global_load_dwordx2 v[12:13], v[2:3], off offset:96
	s_mul_i32 s36, s26, 3
	s_waitcnt vmcnt(3)
	v_lshlrev_b32_e32 v6, 16, v4
	v_and_b32_e32 v7, 0xffff0000, v4
	v_lshlrev_b32_e32 v4, 16, v5
	v_and_b32_e32 v5, 0xffff0000, v5
	v_pk_fma_f32 v[6:7], v[94:95], v[0:1], v[6:7] op_sel_hi:[1,0,1]
	v_pk_fma_f32 v[4:5], v[96:97], v[0:1], v[4:5] op_sel_hi:[1,0,1]
	v_cvt_pk_bf16_f32 v6, v6, v7
	v_cvt_pk_bf16_f32 v7, v4, v5
	global_store_dwordx2 v[2:3], v[6:7], off
	s_waitcnt vmcnt(3)
	v_lshlrev_b32_e32 v6, 16, v8
	v_and_b32_e32 v7, 0xffff0000, v8
	v_lshlrev_b32_e32 v8, 16, v9
	v_and_b32_e32 v9, 0xffff0000, v9
	v_pk_fma_f32 v[6:7], v[90:91], v[0:1], v[6:7] op_sel_hi:[1,0,1]
	v_pk_fma_f32 v[8:9], v[92:93], v[0:1], v[8:9] op_sel_hi:[1,0,1]
	v_cvt_pk_bf16_f32 v6, v6, v7
	v_cvt_pk_bf16_f32 v7, v8, v9
	global_store_dwordx2 v[2:3], v[6:7], off offset:32
	s_waitcnt vmcnt(3)
	v_lshlrev_b32_e32 v6, 16, v10
	v_and_b32_e32 v7, 0xffff0000, v10
	v_lshlrev_b32_e32 v10, 16, v11
	v_and_b32_e32 v11, 0xffff0000, v11
	v_pk_fma_f32 v[6:7], v[86:87], v[0:1], v[6:7] op_sel_hi:[1,0,1]
	v_pk_fma_f32 v[10:11], v[88:89], v[0:1], v[10:11] op_sel_hi:[1,0,1]
	v_cvt_pk_bf16_f32 v6, v6, v7
	v_cvt_pk_bf16_f32 v7, v10, v11
	global_store_dwordx2 v[2:3], v[6:7], off offset:64
	s_waitcnt vmcnt(3)
	v_lshlrev_b32_e32 v6, 16, v12
	v_and_b32_e32 v7, 0xffff0000, v12
	v_lshlrev_b32_e32 v12, 16, v13
	v_and_b32_e32 v13, 0xffff0000, v13
	v_pk_fma_f32 v[6:7], v[82:83], v[0:1], v[6:7] op_sel_hi:[1,0,1]
	v_pk_fma_f32 v[12:13], v[84:85], v[0:1], v[12:13] op_sel_hi:[1,0,1]
	v_cvt_pk_bf16_f32 v6, v6, v7
	v_cvt_pk_bf16_f32 v7, v12, v13
	global_store_dwordx2 v[2:3], v[6:7], off offset:96
	v_lshl_add_u64 v[2:3], s[36:37], 2, v[130:131]
	global_load_dword v0, v[2:3], off offset:4
	ds_bpermute_b32 v2, v106, v117
	s_lshl_b32 s36, s21, 1
	s_waitcnt lgkmcnt(0)
	v_add_f32_e32 v2, v117, v2
	ds_bpermute_b32 v3, v107, v2
	s_waitcnt lgkmcnt(0)
	v_add_f32_e32 v2, v2, v3
	v_div_scale_f32 v3, s[26:27], v2, v2, 1.0
	v_rcp_f32_e32 v4, v3
	v_cmp_lt_f32_e64 s[0:1], 0, v2
	v_fma_f32 v5, -v3, v4, 1.0
	v_fmac_f32_e32 v4, v5, v4
	v_div_scale_f32 v5, vcc, 1.0, v2, 1.0
	v_mul_f32_e32 v6, v5, v4
	v_fma_f32 v7, -v3, v6, v5
	v_fmac_f32_e32 v6, v7, v4
	v_fma_f32 v3, -v3, v6, v5
	v_div_fmas_f32 v3, v3, v4, v6
	v_div_fixup_f32 v2, v3, v2, 1.0
	v_cndmask_b32_e64 v2, 0, v2, s[0:1]
	s_mov_b64 s[0:1], 0
	s_and_b64 vcc, exec, s[28:29]
	s_waitcnt vmcnt(0)
	v_mul_f32_e32 v0, v0, v2
	v_lshl_add_u64 v[2:3], v[136:137], 0, s[36:37]
	global_load_dwordx2 v[4:5], v[2:3], off
	global_load_dwordx2 v[8:9], v[2:3], off offset:32
	global_load_dwordx2 v[10:11], v[2:3], off offset:64
	global_load_dwordx2 v[12:13], v[2:3], off offset:96
	s_waitcnt vmcnt(3)
	v_lshlrev_b32_e32 v6, 16, v4
	v_and_b32_e32 v7, 0xffff0000, v4
	v_lshlrev_b32_e32 v4, 16, v5
	v_and_b32_e32 v5, 0xffff0000, v5
	v_pk_fma_f32 v[6:7], v[74:75], v[0:1], v[6:7] op_sel_hi:[1,0,1]
	v_pk_fma_f32 v[4:5], v[76:77], v[0:1], v[4:5] op_sel_hi:[1,0,1]
	v_cvt_pk_bf16_f32 v6, v6, v7
	v_cvt_pk_bf16_f32 v7, v4, v5
	global_store_dwordx2 v[2:3], v[6:7], off
	s_waitcnt vmcnt(3)
	v_lshlrev_b32_e32 v6, 16, v8
	v_and_b32_e32 v7, 0xffff0000, v8
	v_lshlrev_b32_e32 v8, 16, v9
	v_and_b32_e32 v9, 0xffff0000, v9
	v_pk_fma_f32 v[6:7], v[78:79], v[0:1], v[6:7] op_sel_hi:[1,0,1]
	v_pk_fma_f32 v[8:9], v[80:81], v[0:1], v[8:9] op_sel_hi:[1,0,1]
	v_cvt_pk_bf16_f32 v6, v6, v7
	v_cvt_pk_bf16_f32 v7, v8, v9
	global_store_dwordx2 v[2:3], v[6:7], off offset:32
	s_waitcnt vmcnt(3)
	v_lshlrev_b32_e32 v6, 16, v10
	v_and_b32_e32 v7, 0xffff0000, v10
	v_lshlrev_b32_e32 v10, 16, v11
	v_and_b32_e32 v11, 0xffff0000, v11
	v_pk_fma_f32 v[6:7], v[70:71], v[0:1], v[6:7] op_sel_hi:[1,0,1]
	v_pk_fma_f32 v[10:11], v[72:73], v[0:1], v[10:11] op_sel_hi:[1,0,1]
	v_cvt_pk_bf16_f32 v6, v6, v7
	v_cvt_pk_bf16_f32 v7, v10, v11
	global_store_dwordx2 v[2:3], v[6:7], off offset:64
	s_waitcnt vmcnt(3)
	v_lshlrev_b32_e32 v6, 16, v12
	v_and_b32_e32 v7, 0xffff0000, v12
	v_lshlrev_b32_e32 v12, 16, v13
	v_and_b32_e32 v13, 0xffff0000, v13
	v_pk_fma_f32 v[6:7], v[66:67], v[0:1], v[6:7] op_sel_hi:[1,0,1]
	v_pk_fma_f32 v[12:13], v[68:69], v[0:1], v[12:13] op_sel_hi:[1,0,1]
	v_cvt_pk_bf16_f32 v6, v6, v7
	v_cvt_pk_bf16_f32 v7, v12, v13
	global_store_dwordx2 v[2:3], v[6:7], off offset:96
	s_barrier
	s_cbranch_vccnz .LBB0_315
